# chain K-loop: LDS-DMA source addresses kept as running per-lane addresses, bumped inside the MFMA block (no address VALU in load segments)
# baseline (speedup 1.0000x reference)
.LBB0_2157:
	s_cmp_lt_u32 s94, 5
	s_cbranch_scc1 .LBB0_2169
	s_add_i32 s51, s94, -2
	s_add_u32 s10, s36, s12
	s_addc_u32 s11, s37, s13
	v_lshl_add_u64 v[138:139], s[10:11], 0, v[176:177]
	v_lshl_add_u64 v[140:141], s[10:11], 0, v[174:175]
	s_add_u32 s10, s70, s12
	s_addc_u32 s11, s71, s13
	v_lshl_add_u64 v[142:143], s[10:11], 0, v[178:179]
	v_lshl_add_u64 v[144:145], s[10:11], 0, v[0:1]
	s_mov_b32 s62, 8
	s_mov_b64 s[38:39], 0
	s_mov_b64 s[98:99], 0x80
	v_lshl_add_u64 v[144:145], v[144:145], 0, s[78:79]
	v_lshl_add_u64 v[142:143], v[142:143], 0, s[78:79]
	v_lshl_add_u64 v[130:131], v[130:131], 0, s[76:77]
	v_lshl_add_u64 v[132:133], v[132:133], 0, s[76:77]
	v_lshl_add_u64 v[140:141], v[140:141], 0, s[76:77]
	v_lshl_add_u64 v[138:139], v[138:139], 0, s[76:77]
	v_lshl_add_u64 v[134:135], v[134:135], 0, s[76:77]
	v_lshl_add_u64 v[136:137], v[136:137], 0, s[76:77]

.LBB0_2163:
	ds_read_b128 v[150:153], v146
	ds_read_b128 v[154:157], v146 offset:1024
	ds_read_b128 v[158:161], v146 offset:2048
	ds_read_b128 v[162:165], v146 offset:3072
	ds_read_b128 v[166:169], v147
	ds_read_b128 v[180:183], v147 offset:1024
	ds_read_b128 v[184:187], v147 offset:2048
	ds_read_b128 v[188:191], v147 offset:3072
	s_mov_b32 m0, s95
	ds_read_b128 v[192:195], v200
	ds_read_b128 v[196:199], v200 offset:1024
	ds_read_b128 v[218:221], v200 offset:2048
	ds_read_b128 v[222:225], v200 offset:3072
	ds_read_b128 v[226:229], v200 offset:4096
	ds_read_b128 v[230:233], v200 offset:5120
	ds_read_b128 v[234:237], v200 offset:6144
	ds_read_b128 v[238:241], v200 offset:7168
	global_load_lds_dwordx4 v[144:145], off
	s_mov_b32 m0, s96
	s_nop 0
	global_load_lds_dwordx4 v[142:143], off
	s_waitcnt vmcnt(8)
	s_waitcnt lgkmcnt(0)
	s_barrier
	s_setprio 1
	s_waitcnt lgkmcnt(0)
	v_mfma_f32_16x16x32_bf16 v[126:129], v[150:153], v[192:195], v[126:129]
	v_mfma_f32_16x16x32_bf16 v[122:125], v[158:161], v[192:195], v[122:125]
	v_lshl_add_u64 v[144:145], v[144:145], 0, s[98:99]
	v_mfma_f32_16x16x32_bf16 v[118:121], v[150:153], v[218:221], v[118:121]
	v_mfma_f32_16x16x32_bf16 v[114:117], v[158:161], v[218:221], v[114:117]
	v_mfma_f32_16x16x32_bf16 v[110:113], v[150:153], v[226:229], v[110:113]
	v_mfma_f32_16x16x32_bf16 v[106:109], v[158:161], v[226:229], v[106:109]
	v_lshl_add_u64 v[142:143], v[142:143], 0, s[98:99]
	v_mfma_f32_16x16x32_bf16 v[102:105], v[150:153], v[234:237], v[102:105]
	v_mfma_f32_16x16x32_bf16 v[98:101], v[158:161], v[234:237], v[98:101]
	v_mfma_f32_16x16x32_bf16 v[126:129], v[154:157], v[196:199], v[126:129]
	v_mfma_f32_16x16x32_bf16 v[122:125], v[162:165], v[196:199], v[122:125]
	v_mfma_f32_16x16x32_bf16 v[118:121], v[154:157], v[222:225], v[118:121]
	v_mfma_f32_16x16x32_bf16 v[114:117], v[162:165], v[222:225], v[114:117]
	v_mfma_f32_16x16x32_bf16 v[110:113], v[154:157], v[230:233], v[110:113]
	v_mfma_f32_16x16x32_bf16 v[106:109], v[162:165], v[230:233], v[106:109]
	v_mfma_f32_16x16x32_bf16 v[102:105], v[154:157], v[238:241], v[102:105]
	v_mfma_f32_16x16x32_bf16 v[98:101], v[162:165], v[238:241], v[98:101]
	s_setprio 0
	s_setprio 1
	v_mfma_f32_16x16x32_bf16 v[94:97], v[166:169], v[192:195], v[94:97]
	v_mfma_f32_16x16x32_bf16 v[90:93], v[184:187], v[192:195], v[90:93]
	v_mfma_f32_16x16x32_bf16 v[86:89], v[166:169], v[218:221], v[86:89]
	v_mfma_f32_16x16x32_bf16 v[82:85], v[184:187], v[218:221], v[82:85]
	v_mfma_f32_16x16x32_bf16 v[78:81], v[166:169], v[226:229], v[78:81]
	v_mfma_f32_16x16x32_bf16 v[74:77], v[184:187], v[226:229], v[74:77]
	v_mfma_f32_16x16x32_bf16 v[70:73], v[166:169], v[234:237], v[70:73]
	v_mfma_f32_16x16x32_bf16 v[66:69], v[184:187], v[234:237], v[66:69]
	v_mfma_f32_16x16x32_bf16 v[94:97], v[180:183], v[196:199], v[94:97]
	v_mfma_f32_16x16x32_bf16 v[90:93], v[188:191], v[196:199], v[90:93]
	v_mfma_f32_16x16x32_bf16 v[86:89], v[180:183], v[222:225], v[86:89]
	v_mfma_f32_16x16x32_bf16 v[82:85], v[188:191], v[222:225], v[82:85]
	v_mfma_f32_16x16x32_bf16 v[78:81], v[180:183], v[230:233], v[78:81]
	v_mfma_f32_16x16x32_bf16 v[74:77], v[188:191], v[230:233], v[74:77]
	v_mfma_f32_16x16x32_bf16 v[70:73], v[180:183], v[238:241], v[70:73]
	v_mfma_f32_16x16x32_bf16 v[66:69], v[188:191], v[238:241], v[66:69]
	s_setprio 0
	s_barrier
	s_mov_b32 m0, s2
	ds_read_b128 v[192:195], v200 offset:16384
	ds_read_b128 v[196:199], v200 offset:17408
	ds_read_b128 v[218:221], v200 offset:18432
	ds_read_b128 v[222:225], v200 offset:19456
	ds_read_b128 v[226:229], v200 offset:20480
	ds_read_b128 v[230:233], v200 offset:21504
	ds_read_b128 v[234:237], v200 offset:22528
	ds_read_b128 v[238:241], v200 offset:23552
	global_load_lds_dwordx4 v[130:131], off
	s_mov_b32 m0, s56
	s_nop 0
	global_load_lds_dwordx4 v[132:133], off
	s_mov_b32 m0, s19
	s_nop 0
	global_load_lds_dwordx4 v[140:141], off
	s_mov_b32 m0, s63
	s_nop 0
	global_load_lds_dwordx4 v[138:139], off
	s_mov_b32 m0, s53
	s_nop 0
	global_load_lds_dwordx4 v[134:135], off
	s_mov_b32 m0, s92
	s_nop 0
	global_load_lds_dwordx4 v[136:137], off
	s_waitcnt vmcnt(8)
	s_waitcnt lgkmcnt(0)
	s_barrier
	s_setprio 1
	s_waitcnt lgkmcnt(0)
	v_mfma_f32_16x16x32_bf16 v[62:65], v[150:153], v[192:195], v[62:65]
	v_mfma_f32_16x16x32_bf16 v[58:61], v[158:161], v[192:195], v[58:61]
	v_lshl_add_u64 v[130:131], v[130:131], 0, s[98:99]
	v_mfma_f32_16x16x32_bf16 v[54:57], v[150:153], v[218:221], v[54:57]
	v_mfma_f32_16x16x32_bf16 v[50:53], v[158:161], v[218:221], v[50:53]
	v_mfma_f32_16x16x32_bf16 v[46:49], v[150:153], v[226:229], v[46:49]
	v_mfma_f32_16x16x32_bf16 v[42:45], v[158:161], v[226:229], v[42:45]
	v_lshl_add_u64 v[132:133], v[132:133], 0, s[98:99]
	v_mfma_f32_16x16x32_bf16 v[38:41], v[150:153], v[234:237], v[38:41]
	v_mfma_f32_16x16x32_bf16 v[34:37], v[158:161], v[234:237], v[34:37]
	v_mfma_f32_16x16x32_bf16 v[62:65], v[154:157], v[196:199], v[62:65]
	v_mfma_f32_16x16x32_bf16 v[58:61], v[162:165], v[196:199], v[58:61]
	v_lshl_add_u64 v[140:141], v[140:141], 0, s[98:99]
	v_mfma_f32_16x16x32_bf16 v[54:57], v[154:157], v[222:225], v[54:57]
	v_mfma_f32_16x16x32_bf16 v[50:53], v[162:165], v[222:225], v[50:53]
	v_mfma_f32_16x16x32_bf16 v[46:49], v[154:157], v[230:233], v[46:49]
	v_mfma_f32_16x16x32_bf16 v[42:45], v[162:165], v[230:233], v[42:45]
	v_lshl_add_u64 v[138:139], v[138:139], 0, s[98:99]
	v_mfma_f32_16x16x32_bf16 v[38:41], v[154:157], v[238:241], v[38:41]
	v_mfma_f32_16x16x32_bf16 v[34:37], v[162:165], v[238:241], v[34:37]
	s_setprio 0
	s_setprio 1
	v_mfma_f32_16x16x32_bf16 v[30:33], v[166:169], v[192:195], v[30:33]
	v_mfma_f32_16x16x32_bf16 v[26:29], v[184:187], v[192:195], v[26:29]
	v_lshl_add_u64 v[134:135], v[134:135], 0, s[98:99]
	v_mfma_f32_16x16x32_bf16 v[22:25], v[166:169], v[218:221], v[22:25]
	v_mfma_f32_16x16x32_bf16 v[18:21], v[184:187], v[218:221], v[18:21]
	v_mfma_f32_16x16x32_bf16 v[14:17], v[166:169], v[226:229], v[14:17]
	v_mfma_f32_16x16x32_bf16 v[10:13], v[184:187], v[226:229], v[10:13]
	v_lshl_add_u64 v[136:137], v[136:137], 0, s[98:99]
	v_mfma_f32_16x16x32_bf16 v[6:9], v[166:169], v[234:237], v[6:9]
	v_mfma_f32_16x16x32_bf16 v[2:5], v[184:187], v[234:237], v[2:5]
	v_mfma_f32_16x16x32_bf16 v[30:33], v[180:183], v[196:199], v[30:33]
	v_mfma_f32_16x16x32_bf16 v[26:29], v[188:191], v[196:199], v[26:29]
	v_mfma_f32_16x16x32_bf16 v[22:25], v[180:183], v[222:225], v[22:25]
	v_mfma_f32_16x16x32_bf16 v[18:21], v[188:191], v[222:225], v[18:21]
	v_mfma_f32_16x16x32_bf16 v[14:17], v[180:183], v[230:233], v[14:17]
	v_mfma_f32_16x16x32_bf16 v[10:13], v[188:191], v[230:233], v[10:13]
	v_mfma_f32_16x16x32_bf16 v[6:9], v[180:183], v[238:241], v[6:9]
	v_mfma_f32_16x16x32_bf16 v[2:5], v[188:191], v[238:241], v[2:5]
	s_setprio 0
	s_barrier
	ds_read_b128 v[150:153], v148
	ds_read_b128 v[154:157], v148 offset:1024
	ds_read_b128 v[158:161], v148 offset:2048
	ds_read_b128 v[162:165], v148 offset:3072
	ds_read_b128 v[166:169], v149
	ds_read_b128 v[180:183], v149 offset:1024
	ds_read_b128 v[184:187], v149 offset:2048
	ds_read_b128 v[188:191], v149 offset:3072
	s_mov_b32 m0, s93
	ds_read_b128 v[192:195], v200 offset:32768
	ds_read_b128 v[196:199], v200 offset:33792
	ds_read_b128 v[218:221], v200 offset:34816
	ds_read_b128 v[222:225], v200 offset:35840
	ds_read_b128 v[226:229], v200 offset:36864
	ds_read_b128 v[230:233], v200 offset:37888
	ds_read_b128 v[234:237], v200 offset:38912
	ds_read_b128 v[238:241], v200 offset:39936
	global_load_lds_dwordx4 v[144:145], off
	s_mov_b32 m0, s54
	s_nop 0
	global_load_lds_dwordx4 v[142:143], off
	s_waitcnt vmcnt(8)
	s_waitcnt lgkmcnt(0)
	s_barrier
	s_setprio 1
	s_waitcnt lgkmcnt(0)
	v_mfma_f32_16x16x32_bf16 v[126:129], v[150:153], v[192:195], v[126:129]
	v_mfma_f32_16x16x32_bf16 v[122:125], v[158:161], v[192:195], v[122:125]
	v_lshl_add_u64 v[144:145], v[144:145], 0, s[98:99]
	v_mfma_f32_16x16x32_bf16 v[118:121], v[150:153], v[218:221], v[118:121]
	v_mfma_f32_16x16x32_bf16 v[114:117], v[158:161], v[218:221], v[114:117]
	v_mfma_f32_16x16x32_bf16 v[110:113], v[150:153], v[226:229], v[110:113]
	v_mfma_f32_16x16x32_bf16 v[106:109], v[158:161], v[226:229], v[106:109]
	v_lshl_add_u64 v[142:143], v[142:143], 0, s[98:99]
	v_mfma_f32_16x16x32_bf16 v[102:105], v[150:153], v[234:237], v[102:105]
	v_mfma_f32_16x16x32_bf16 v[98:101], v[158:161], v[234:237], v[98:101]
	v_mfma_f32_16x16x32_bf16 v[126:129], v[154:157], v[196:199], v[126:129]
	v_mfma_f32_16x16x32_bf16 v[122:125], v[162:165], v[196:199], v[122:125]
	v_mfma_f32_16x16x32_bf16 v[118:121], v[154:157], v[222:225], v[118:121]
	v_mfma_f32_16x16x32_bf16 v[114:117], v[162:165], v[222:225], v[114:117]
	v_mfma_f32_16x16x32_bf16 v[110:113], v[154:157], v[230:233], v[110:113]
	v_mfma_f32_16x16x32_bf16 v[106:109], v[162:165], v[230:233], v[106:109]
	v_mfma_f32_16x16x32_bf16 v[102:105], v[154:157], v[238:241], v[102:105]
	v_mfma_f32_16x16x32_bf16 v[98:101], v[162:165], v[238:241], v[98:101]
	s_setprio 0
	s_setprio 1
	v_mfma_f32_16x16x32_bf16 v[94:97], v[166:169], v[192:195], v[94:97]
	v_mfma_f32_16x16x32_bf16 v[90:93], v[184:187], v[192:195], v[90:93]
	v_mfma_f32_16x16x32_bf16 v[86:89], v[166:169], v[218:221], v[86:89]
	v_mfma_f32_16x16x32_bf16 v[82:85], v[184:187], v[218:221], v[82:85]
	v_mfma_f32_16x16x32_bf16 v[78:81], v[166:169], v[226:229], v[78:81]
	v_mfma_f32_16x16x32_bf16 v[74:77], v[184:187], v[226:229], v[74:77]
	v_mfma_f32_16x16x32_bf16 v[70:73], v[166:169], v[234:237], v[70:73]
	v_mfma_f32_16x16x32_bf16 v[66:69], v[184:187], v[234:237], v[66:69]
	v_mfma_f32_16x16x32_bf16 v[94:97], v[180:183], v[196:199], v[94:97]
	v_mfma_f32_16x16x32_bf16 v[90:93], v[188:191], v[196:199], v[90:93]
	v_mfma_f32_16x16x32_bf16 v[86:89], v[180:183], v[222:225], v[86:89]
	v_mfma_f32_16x16x32_bf16 v[82:85], v[188:191], v[222:225], v[82:85]
	v_mfma_f32_16x16x32_bf16 v[78:81], v[180:183], v[230:233], v[78:81]
	v_mfma_f32_16x16x32_bf16 v[74:77], v[188:191], v[230:233], v[74:77]
	v_mfma_f32_16x16x32_bf16 v[70:73], v[180:183], v[238:241], v[70:73]
	v_mfma_f32_16x16x32_bf16 v[66:69], v[188:191], v[238:241], v[66:69]
	s_setprio 0
	s_barrier
	s_mov_b32 m0, s33
	ds_read_b128 v[192:195], v200 offset:49152
	ds_read_b128 v[196:199], v200 offset:50176
	ds_read_b128 v[218:221], v200 offset:51200
	ds_read_b128 v[222:225], v200 offset:52224
	ds_read_b128 v[226:229], v200 offset:53248
	ds_read_b128 v[230:233], v200 offset:54272
	ds_read_b128 v[234:237], v200 offset:55296
	ds_read_b128 v[238:241], v200 offset:56320
	global_load_lds_dwordx4 v[130:131], off
	s_mov_b32 m0, s3
	s_nop 0
	global_load_lds_dwordx4 v[132:133], off
	s_mov_b32 m0, s47
	s_nop 0
	global_load_lds_dwordx4 v[140:141], off
	s_mov_b32 m0, s4
	s_nop 0
	global_load_lds_dwordx4 v[138:139], off
	s_mov_b32 m0, s55
	s_nop 0
	global_load_lds_dwordx4 v[134:135], off
	s_mov_b32 m0, s64
	s_nop 0
	global_load_lds_dwordx4 v[136:137], off
	s_waitcnt vmcnt(8)
	s_waitcnt lgkmcnt(0)
	s_barrier
	s_setprio 1
	s_waitcnt lgkmcnt(0)
	v_mfma_f32_16x16x32_bf16 v[62:65], v[150:153], v[192:195], v[62:65]
	v_mfma_f32_16x16x32_bf16 v[58:61], v[158:161], v[192:195], v[58:61]
	v_lshl_add_u64 v[130:131], v[130:131], 0, s[98:99]
	v_mfma_f32_16x16x32_bf16 v[54:57], v[150:153], v[218:221], v[54:57]
	v_mfma_f32_16x16x32_bf16 v[50:53], v[158:161], v[218:221], v[50:53]
	v_mfma_f32_16x16x32_bf16 v[46:49], v[150:153], v[226:229], v[46:49]
	v_mfma_f32_16x16x32_bf16 v[42:45], v[158:161], v[226:229], v[42:45]
	v_lshl_add_u64 v[132:133], v[132:133], 0, s[98:99]
	v_mfma_f32_16x16x32_bf16 v[38:41], v[150:153], v[234:237], v[38:41]
	v_mfma_f32_16x16x32_bf16 v[34:37], v[158:161], v[234:237], v[34:37]
	v_mfma_f32_16x16x32_bf16 v[62:65], v[154:157], v[196:199], v[62:65]
	v_mfma_f32_16x16x32_bf16 v[58:61], v[162:165], v[196:199], v[58:61]
	v_lshl_add_u64 v[140:141], v[140:141], 0, s[98:99]
	v_mfma_f32_16x16x32_bf16 v[54:57], v[154:157], v[222:225], v[54:57]
	v_mfma_f32_16x16x32_bf16 v[50:53], v[162:165], v[222:225], v[50:53]
	v_mfma_f32_16x16x32_bf16 v[46:49], v[154:157], v[230:233], v[46:49]
	v_mfma_f32_16x16x32_bf16 v[42:45], v[162:165], v[230:233], v[42:45]
	v_lshl_add_u64 v[138:139], v[138:139], 0, s[98:99]
	v_mfma_f32_16x16x32_bf16 v[38:41], v[154:157], v[238:241], v[38:41]
	v_mfma_f32_16x16x32_bf16 v[34:37], v[162:165], v[238:241], v[34:37]
	s_setprio 0
	s_setprio 1
	v_mfma_f32_16x16x32_bf16 v[30:33], v[166:169], v[192:195], v[30:33]
	v_mfma_f32_16x16x32_bf16 v[26:29], v[184:187], v[192:195], v[26:29]
	v_lshl_add_u64 v[134:135], v[134:135], 0, s[98:99]
	v_mfma_f32_16x16x32_bf16 v[22:25], v[166:169], v[218:221], v[22:25]
	v_mfma_f32_16x16x32_bf16 v[18:21], v[184:187], v[218:221], v[18:21]
	v_mfma_f32_16x16x32_bf16 v[14:17], v[166:169], v[226:229], v[14:17]
	v_mfma_f32_16x16x32_bf16 v[10:13], v[184:187], v[226:229], v[10:13]
	v_lshl_add_u64 v[136:137], v[136:137], 0, s[98:99]
	v_mfma_f32_16x16x32_bf16 v[6:9], v[166:169], v[234:237], v[6:9]
	v_mfma_f32_16x16x32_bf16 v[2:5], v[184:187], v[234:237], v[2:5]
	v_mfma_f32_16x16x32_bf16 v[30:33], v[180:183], v[196:199], v[30:33]
	v_mfma_f32_16x16x32_bf16 v[26:29], v[188:191], v[196:199], v[26:29]
	v_mfma_f32_16x16x32_bf16 v[22:25], v[180:183], v[222:225], v[22:25]
	v_mfma_f32_16x16x32_bf16 v[18:21], v[188:191], v[222:225], v[18:21]
	v_mfma_f32_16x16x32_bf16 v[14:17], v[180:183], v[230:233], v[14:17]
	v_mfma_f32_16x16x32_bf16 v[10:13], v[188:191], v[230:233], v[10:13]
	v_mfma_f32_16x16x32_bf16 v[6:9], v[180:183], v[238:241], v[6:9]
	v_mfma_f32_16x16x32_bf16 v[2:5], v[188:191], v[238:241], v[2:5]
	s_setprio 0
	s_barrier
	s_and_b64 vcc, exec, s[10:11]
	s_cbranch_vccnz .LBB0_2166
	s_waitcnt vmcnt(16)
	v_mov_b32_e32 v150, s50
	v_mov_b32_e32 v151, s5
	ds_read_b32 v150, v150
	ds_read_b32 v151, v151 offset:60
	s_mov_b64 s[40:41], 0
	s_waitcnt lgkmcnt(0)
	v_readfirstlane_b32 s10, v150
	v_readfirstlane_b32 s11, v151
	s_mul_i32 s11, s11, s18
	s_cmp_lt_u32 s10, s11
	s_cbranch_scc1 .LBB0_2166
	buffer_inv sc1
	s_mov_b64 s[40:41], -1
